# code placement: GEMM K-loop head aligned to 64 bytes
# speedup vs baseline: 1.0030x; 1.0015x over previous
; __device__ __forceinline__ long a_row0(const Gemm& g, int pm) { if (!g.ffn) return (long)pm * BM; int tok0; ffn_tile(pm, tok0); return (long)tok0; }
; #define PG8_BAR __builtin_amdgcn_s_barrier()
; __device__ __forceinline__ void gemm_phase(LAS unsigned char* lds, const Gemm g, const StaticOrder& S, const Epi& E, const int tid) {
;     ...
;     for (;;) {
;         const bool has_next = S.next(ui + 1, nxt);
;         const char* nA = has_next ? (const char*)g.A + a_row0(g, nxt.pm) * rowbA : cA; const char* nB = has_next ? (const char*)g.Bt + (size_t)nxt.pn * tstepB : cB;
;         for (int t = 0; t < nt; t += 2) {
;             const bool last = (t == nt - 2);
;             const char* a1 = cA + (size_t)(t + 1) * kstep;
;             const char* a2 = last ? nA : cA + (size_t)(t + 2) * kstep; const char* b2 = last ? nB : cB + (size_t)(t + 2) * kstep;
;             const char* a3 = a2 + kstep; const char* b3 = b2 + kstep;
;     ...
; #pragma unroll
;         for (int a = 0; a < 2; ++a)
; #pragma unroll
;             for (int b = 0; b < 2; ++b)
; #pragma unroll
;                 for (int m = 0; m < 4; ++m)
; #pragma unroll
;                     for (int n = 0; n < 2; ++n) acc[a][b][m][n] = (f32x4){0.f, 0.f, 0.f, 0.f};
;         cur = nxt; cA = nA; cB = nB; ++ui;
;         if (wr == 1) PG8_BAR;
.LBB0_528:
	v_readlane_b32 s18, v254, 62
	v_mov_b64_e32 v[2:3], 0
	v_mov_b64_e32 v[4:5], 0
	v_mov_b64_e32 v[6:7], 0
	v_mov_b64_e32 v[8:9], 0
	v_mov_b64_e32 v[10:11], 0
	v_mov_b64_e32 v[12:13], 0
	v_mov_b64_e32 v[14:15], 0
	v_mov_b64_e32 v[16:17], 0
	v_mov_b64_e32 v[18:19], 0
	v_mov_b64_e32 v[20:21], 0
	v_mov_b64_e32 v[22:23], 0
	v_mov_b64_e32 v[24:25], 0
	v_mov_b64_e32 v[26:27], 0
	v_mov_b64_e32 v[28:29], 0
	v_mov_b64_e32 v[30:31], 0
	v_mov_b64_e32 v[32:33], 0
	v_mov_b64_e32 v[34:35], 0
	v_mov_b64_e32 v[36:37], 0
	v_mov_b64_e32 v[38:39], 0
	v_mov_b64_e32 v[40:41], 0
	v_mov_b64_e32 v[42:43], 0
	v_mov_b64_e32 v[44:45], 0
	v_mov_b64_e32 v[46:47], 0
	v_mov_b64_e32 v[48:49], 0
	v_mov_b64_e32 v[50:51], 0
	v_mov_b64_e32 v[52:53], 0
	v_mov_b64_e32 v[54:55], 0
	v_mov_b64_e32 v[56:57], 0
	v_mov_b64_e32 v[58:59], 0
	v_mov_b64_e32 v[60:61], 0
	v_mov_b64_e32 v[62:63], 0
	v_mov_b64_e32 v[64:65], 0
	v_mov_b64_e32 v[66:67], 0
	v_mov_b64_e32 v[68:69], 0
	v_mov_b64_e32 v[70:71], 0
	v_mov_b64_e32 v[72:73], 0
	v_mov_b64_e32 v[74:75], 0
	v_mov_b64_e32 v[76:77], 0
	v_mov_b64_e32 v[78:79], 0
	v_mov_b64_e32 v[80:81], 0
	v_mov_b64_e32 v[82:83], 0
	v_mov_b64_e32 v[84:85], 0
	v_mov_b64_e32 v[86:87], 0
	v_mov_b64_e32 v[88:89], 0
	v_mov_b64_e32 v[90:91], 0
	v_mov_b64_e32 v[92:93], 0
	v_mov_b64_e32 v[94:95], 0
	v_mov_b64_e32 v[96:97], 0
	v_mov_b64_e32 v[98:99], 0
	v_mov_b64_e32 v[100:101], 0
	v_mov_b64_e32 v[102:103], 0
	v_mov_b64_e32 v[104:105], 0
	v_mov_b64_e32 v[106:107], 0
	v_mov_b64_e32 v[108:109], 0
	v_mov_b64_e32 v[110:111], 0
	v_mov_b64_e32 v[112:113], 0
	v_mov_b64_e32 v[114:115], 0
	v_mov_b64_e32 v[116:117], 0
	v_mov_b64_e32 v[118:119], 0
	v_mov_b64_e32 v[120:121], 0
	v_mov_b64_e32 v[122:123], 0
	v_mov_b64_e32 v[124:125], 0
	v_mov_b64_e32 v[126:127], 0
	v_mov_b64_e32 v[128:129], 0
	v_readlane_b32 s19, v254, 63
	s_andn2_b64 vcc, exec, s[18:19]
	s_cbranch_vccnz .LBB0_531
	s_add_u32 s2, s2, 0x80
	s_addc_u32 s3, s3, 0
	s_add_u32 s18, s4, 0x100
	s_addc_u32 s19, s5, 0
	s_mov_b32 s4, 0
	.p2align 6
